# P1 epilogue: SSX row-sum loads for the next 16-row block issued one block ahead (fresh VGPRs), counted vmcnt so a block no longer drains the previous block's Z stores
# baseline (speedup 1.0000x reference)
; DI u32x2 pack4(f32x4 v) { return u32x2{pack2(v[0], v[1]), pack2(v[2], v[3])}; }
; DI void phase1(const XcdMap xm, const int wv, const Params& p0, int l, char* s0, char* s1, char* s2) {
;     ...
; #pragma unroll
;     for (int mt = 0; mt < 4; ++mt) {
;       const int m = m0 + wr * 64 + mt * 16 + c16;
;       f32x4 s0 = ld4(ssx + (size_t)m * 16), s1 = ld4(ssx + (size_t)m * 16 + 4), s2 = ld4(ssx + (size_t)m * 16 + 8), s3 = ld4(ssx + (size_t)m * 16 + 12);
;       f32x4 st = s0 + s1 + s2 + s3;
;       const float rs = rsqrtf((st[0] + st[1] + st[2] + st[3]) * (1.f / 1024.f) + 1e-6f);
;       float psum = 0.f;
; #pragma unroll
;       for (int nt = 0; nt < 8; nt += 2) {
;         const int n = n0 + wc * 128 + g * 32 + nt * 4;
;         f32x4 v0 = acc[mt][nt] * rs, v1 = acc[mt][nt + 1] * rs;
;         psum += sum4sq(v0) + sum4sq(v1);
;         u32x2 a = pack4(v0), b = pack4(v1);
;         *(u32x4*)(z + (size_t)m * ZC + n) = u32x4{a.x, a.y, b.x, b.y};
;       }
;       const bool isq = (ntile == 8 && wc == 1) || ntile == 9;
;       if (isq || ntile == 10) {
;         psum = xor_sum(psum, 16);
;         psum = xor_sum(psum, 32);
;         if (g == 0) {
;           if (isq) ((float*)(p.ws + WS_SSQ))[(size_t)m * 8 + (ntile == 8 ? 0 : 1 + wc)] = psum;
;           else ((float*)(p.ws + WS_SSKV))[(size_t)m * 4 + wc] = psum;
;         }
;       }
;     }
.LBB0_931:
	v_add_u32_e32 v158, s2, v191
	v_ashrrev_i32_e32 v159, 31, v158
	v_lshlrev_b64 v[160:161], 6, v[158:159]
	v_lshl_add_u64 v[164:165], s[44:45], 0, v[160:161]
	s_waitcnt vmcnt(0)
	flat_load_dwordx4 v[160:163], v[164:165]
	flat_load_dwordx4 v[172:175], v[164:165] offset:16
	flat_load_dwordx4 v[194:197], v[164:165] offset:32
	flat_load_dwordx4 v[198:201], v[164:165] offset:48
	v_or_b32_e32 v238, 16, v158
	v_ashrrev_i32_e32 v239, 31, v238
	v_lshlrev_b64 v[240:241], 6, v[238:239]
	v_lshl_add_u64 v[240:241], s[44:45], 0, v[240:241]
	flat_load_dwordx4 v[206:209], v[240:241]
	flat_load_dwordx4 v[210:213], v[240:241] offset:16
	flat_load_dwordx4 v[214:217], v[240:241] offset:32
	flat_load_dwordx4 v[218:221], v[240:241] offset:48
	s_cmp_eq_u32 s28, 8
	s_cselect_b64 s[8:9], -1, 0
	s_and_b64 s[20:21], s[38:39], s[8:9]
	v_cndmask_b32_e64 v0, v193, 0, s[8:9]
	s_cmp_eq_u32 s28, 9
	v_lshlrev_b32_e32 v0, 2, v0
	v_or_b32_e32 v156, s42, v192
	s_cselect_b64 s[42:43], -1, 0
	v_lshl_add_u64 v[2:3], s[46:47], 0, v[0:1]
	s_or_b64 vcc, s[42:43], s[20:21]
	s_add_i32 s28, s28, -9
	s_cmp_lt_u32 s28, 2
	s_cselect_b64 s[42:43], -1, 0
	s_or_b64 s[52:53], s[20:21], s[42:43]
	s_waitcnt vmcnt(4)
	v_pk_add_f32 v[160:161], v[160:161], v[172:173]
	v_pk_add_f32 v[162:163], v[162:163], v[174:175]
	v_pk_add_f32 v[160:161], v[160:161], v[194:195]
	v_pk_add_f32 v[162:163], v[162:163], v[196:197]
	v_pk_add_f32 v[160:161], v[160:161], v[198:199]
	v_pk_add_f32 v[162:163], v[162:163], v[200:201]
	v_add_f32_e32 v0, v160, v161
	v_add_f32_e32 v0, v162, v0
	v_add_f32_e32 v0, v163, v0
	v_fmamk_f32 v0, v0, 0x3a800000, v132
	v_cmp_gt_f32_e64 s[42:43], s22, v0
	v_mul_f32_e32 v157, 0x4b800000, v0
	v_mov_b64_e32 v[160:161], s[14:15]
	v_cndmask_b32_e64 v0, v0, v157, s[42:43]
	v_rsq_f32_e32 v0, v0
	v_mad_i64_i32 v[164:165], s[8:9], v158, s23, v[160:161]
	v_mul_f32_e32 v157, 0x45800000, v0
	v_cndmask_b32_e64 v0, v0, v157, s[42:43]
	v_pk_mul_f32 v[130:131], v[130:131], v[0:1] op_sel_hi:[1,0]
	v_pk_mul_f32 v[128:129], v[128:129], v[0:1] op_sel_hi:[1,0]
	v_pk_mul_f32 v[126:127], v[126:127], v[0:1] op_sel_hi:[1,0]
	v_pk_mul_f32 v[124:125], v[124:125], v[0:1] op_sel_hi:[1,0]
	v_ashrrev_i32_e32 v157, 31, v156
	v_cvt_pk_bf16_f32 v160, v128, v129
	v_cvt_pk_bf16_f32 v161, v130, v131
	v_cvt_pk_bf16_f32 v162, v124, v125
	v_cvt_pk_bf16_f32 v163, v126, v127
	v_lshl_add_u64 v[164:165], v[156:157], 1, v[164:165]
	v_pk_mul_f32 v[122:123], v[122:123], v[0:1] op_sel_hi:[1,0]
	v_pk_mul_f32 v[120:121], v[120:121], v[0:1] op_sel_hi:[1,0]
	v_pk_mul_f32 v[118:119], v[118:119], v[0:1] op_sel_hi:[1,0]
	v_pk_mul_f32 v[116:117], v[116:117], v[0:1] op_sel_hi:[1,0]
	flat_store_dwordx4 v[164:165], v[160:163]
	v_pk_mul_f32 v[114:115], v[114:115], v[0:1] op_sel_hi:[1,0]
	v_pk_mul_f32 v[112:113], v[112:113], v[0:1] op_sel_hi:[1,0]
	v_cvt_pk_bf16_f32 v160, v120, v121
	v_cvt_pk_bf16_f32 v161, v122, v123
	v_cvt_pk_bf16_f32 v162, v116, v117
	v_cvt_pk_bf16_f32 v163, v118, v119
	v_pk_mul_f32 v[110:111], v[110:111], v[0:1] op_sel_hi:[1,0]
	v_pk_mul_f32 v[108:109], v[108:109], v[0:1] op_sel_hi:[1,0]
	flat_store_dwordx4 v[164:165], v[160:163] offset:16
	v_pk_mul_f32 v[106:107], v[106:107], v[0:1] op_sel_hi:[1,0]
	v_pk_mul_f32 v[104:105], v[104:105], v[0:1] op_sel_hi:[1,0]
	v_cvt_pk_bf16_f32 v160, v112, v113
	v_cvt_pk_bf16_f32 v161, v114, v115
	v_cvt_pk_bf16_f32 v162, v108, v109
	v_cvt_pk_bf16_f32 v163, v110, v111
	v_pk_mul_f32 v[102:103], v[102:103], v[0:1] op_sel_hi:[1,0]
	v_pk_mul_f32 v[100:101], v[100:101], v[0:1] op_sel_hi:[1,0]
	flat_store_dwordx4 v[164:165], v[160:163] offset:32
	s_nop 1
	v_cvt_pk_bf16_f32 v160, v104, v105
	v_cvt_pk_bf16_f32 v161, v106, v107
	v_cvt_pk_bf16_f32 v162, v100, v101
	v_cvt_pk_bf16_f32 v163, v102, v103
	flat_store_dwordx4 v[164:165], v[160:163] offset:48
	s_and_saveexec_b64 s[8:9], s[52:53]
	s_cbranch_execz .LBB0_934
	v_mul_f32_e32 v0, v129, v129
	v_mul_f32_e32 v125, v125, v125
	v_mul_f32_e32 v121, v121, v121
	v_mul_f32_e32 v117, v117, v117
	v_fmac_f32_e32 v0, v128, v128
	v_fmac_f32_e32 v125, v124, v124
	v_fmac_f32_e32 v121, v120, v120
	v_fmac_f32_e32 v117, v116, v116
	v_mul_f32_e32 v113, v113, v113
	v_mul_f32_e32 v109, v109, v109
	v_fmac_f32_e32 v0, v130, v130
	v_fmac_f32_e32 v125, v126, v126
	v_fmac_f32_e32 v121, v122, v122
	v_fmac_f32_e32 v117, v118, v118
	v_fmac_f32_e32 v113, v112, v112
	v_fmac_f32_e32 v109, v108, v108
	v_mul_f32_e32 v105, v105, v105
	v_mul_f32_e32 v101, v101, v101
	v_fmac_f32_e32 v0, v131, v131
	v_fmac_f32_e32 v125, v127, v127
	v_fmac_f32_e32 v121, v123, v123
	v_fmac_f32_e32 v117, v119, v119
	v_fmac_f32_e32 v113, v114, v114
	v_fmac_f32_e32 v109, v110, v110
	v_fmac_f32_e32 v105, v104, v104
	v_fmac_f32_e32 v101, v100, v100
	v_add_f32_e32 v0, v0, v125
	v_add_f32_e32 v116, v121, v117
	v_fmac_f32_e32 v113, v115, v115
	v_fmac_f32_e32 v109, v111, v111
	v_fmac_f32_e32 v105, v106, v106
	v_fmac_f32_e32 v101, v102, v102
	v_add_f32_e32 v0, v0, v116
	v_add_f32_e32 v108, v113, v109
	v_fmac_f32_e32 v105, v107, v107
	v_fmac_f32_e32 v101, v103, v103
	v_add_f32_e32 v0, v108, v0
	v_add_f32_e32 v100, v105, v101
	v_add_f32_e32 v0, v100, v0
	v_mov_b32_e32 v100, v0
	s_nop 1
	v_permlane16_swap_b32_e32 v0, v100
	v_add_f32_e32 v0, v0, v100
	v_mov_b32_e32 v100, v0
	s_nop 1
	v_permlane32_swap_b32_e32 v0, v100
	s_and_b64 exec, exec, s[40:41]
	s_cbranch_execz .LBB0_934
	v_cndmask_b32_e64 v101, 4, 5, vcc
	v_cndmask_b32_e32 v103, v143, v3, vcc
	v_cndmask_b32_e32 v102, v142, v2, vcc
	v_lshlrev_b64 v[104:105], v101, v[158:159]
	v_lshl_add_u64 v[102:103], v[102:103], 0, v[104:105]
	v_add_f32_e32 v0, v0, v100
	flat_store_dword v[102:103], v0
; DI u32x2 pack4(f32x4 v) { return u32x2{pack2(v[0], v[1]), pack2(v[2], v[3])}; }
; DI void phase1(const XcdMap xm, const int wv, const Params& p0, int l, char* s0, char* s1, char* s2) {
;     ...
; #pragma unroll
;     for (int mt = 0; mt < 4; ++mt) {
;       const int m = m0 + wr * 64 + mt * 16 + c16;
;       f32x4 s0 = ld4(ssx + (size_t)m * 16), s1 = ld4(ssx + (size_t)m * 16 + 4), s2 = ld4(ssx + (size_t)m * 16 + 8), s3 = ld4(ssx + (size_t)m * 16 + 12);
;       f32x4 st = s0 + s1 + s2 + s3;
;       const float rs = rsqrtf((st[0] + st[1] + st[2] + st[3]) * (1.f / 1024.f) + 1e-6f);
;       float psum = 0.f;
; #pragma unroll
;       for (int nt = 0; nt < 8; nt += 2) {
;         const int n = n0 + wc * 128 + g * 32 + nt * 4;
;         f32x4 v0 = acc[mt][nt] * rs, v1 = acc[mt][nt + 1] * rs;
;         psum += sum4sq(v0) + sum4sq(v1);
;         u32x2 a = pack4(v0), b = pack4(v1);
;         *(u32x4*)(z + (size_t)m * ZC + n) = u32x4{a.x, a.y, b.x, b.y};
;       }
;       const bool isq = (ntile == 8 && wc == 1) || ntile == 9;
;       if (isq || ntile == 10) {
;         psum = xor_sum(psum, 16);
;         psum = xor_sum(psum, 32);
;         if (g == 0) {
;           if (isq) ((float*)(p.ws + WS_SSQ))[(size_t)m * 8 + (ntile == 8 ? 0 : 1 + wc)] = psum;
;           else ((float*)(p.ws + WS_SSKV))[(size_t)m * 4 + wc] = psum;
;         }
;       }
;     }
.LBB0_934:
	s_or_b64 exec, exec, s[8:9]
	v_or_b32_e32 v100, 16, v158
	v_ashrrev_i32_e32 v101, 31, v100
	v_or_b32_e32 v238, 32, v158
	v_ashrrev_i32_e32 v239, 31, v238
	v_lshlrev_b64 v[240:241], 6, v[238:239]
	v_lshl_add_u64 v[240:241], s[44:45], 0, v[240:241]
	flat_load_dwordx4 v[222:225], v[240:241]
	flat_load_dwordx4 v[226:229], v[240:241] offset:16
	flat_load_dwordx4 v[230:233], v[240:241] offset:32
	flat_load_dwordx4 v[234:237], v[240:241] offset:48
	s_waitcnt vmcnt(8)
	v_pk_add_f32 v[206:207], v[206:207], v[210:211]
	v_pk_add_f32 v[208:209], v[208:209], v[212:213]
	v_pk_add_f32 v[206:207], v[206:207], v[214:215]
	v_pk_add_f32 v[208:209], v[208:209], v[216:217]
	v_pk_add_f32 v[206:207], v[206:207], v[218:219]
	v_pk_add_f32 v[208:209], v[208:209], v[220:221]
	v_add_f32_e32 v0, v206, v207
	v_add_f32_e32 v0, v208, v0
	v_add_f32_e32 v0, v209, v0
	v_fmamk_f32 v0, v0, 0x3a800000, v132
	v_cmp_gt_f32_e64 s[42:43], s22, v0
	v_mul_f32_e32 v102, 0x4b800000, v0
	s_nop 0
	v_cndmask_b32_e64 v0, v0, v102, s[42:43]
	v_rsq_f32_e32 v0, v0
	s_nop 0
	v_mul_f32_e32 v102, 0x45800000, v0
	v_cndmask_b32_e64 v0, v0, v102, s[42:43]
	v_mov_b64_e32 v[102:103], s[14:15]
	v_mad_i64_i32 v[106:107], s[8:9], v100, s23, v[102:103]
	v_pk_mul_f32 v[98:99], v[98:99], v[0:1] op_sel_hi:[1,0]
	v_pk_mul_f32 v[96:97], v[96:97], v[0:1] op_sel_hi:[1,0]
	v_pk_mul_f32 v[94:95], v[94:95], v[0:1] op_sel_hi:[1,0]
	v_pk_mul_f32 v[92:93], v[92:93], v[0:1] op_sel_hi:[1,0]
	v_cvt_pk_bf16_f32 v102, v96, v97
	v_cvt_pk_bf16_f32 v103, v98, v99
	v_cvt_pk_bf16_f32 v104, v92, v93
	v_cvt_pk_bf16_f32 v105, v94, v95
	v_lshl_add_u64 v[106:107], v[156:157], 1, v[106:107]
	v_pk_mul_f32 v[90:91], v[90:91], v[0:1] op_sel_hi:[1,0]
	v_pk_mul_f32 v[88:89], v[88:89], v[0:1] op_sel_hi:[1,0]
	v_pk_mul_f32 v[86:87], v[86:87], v[0:1] op_sel_hi:[1,0]
	v_pk_mul_f32 v[84:85], v[84:85], v[0:1] op_sel_hi:[1,0]
	flat_store_dwordx4 v[106:107], v[102:105]
	v_pk_mul_f32 v[82:83], v[82:83], v[0:1] op_sel_hi:[1,0]
	v_pk_mul_f32 v[80:81], v[80:81], v[0:1] op_sel_hi:[1,0]
	v_cvt_pk_bf16_f32 v102, v88, v89
	v_cvt_pk_bf16_f32 v103, v90, v91
	v_cvt_pk_bf16_f32 v104, v84, v85
	v_cvt_pk_bf16_f32 v105, v86, v87
	v_pk_mul_f32 v[78:79], v[78:79], v[0:1] op_sel_hi:[1,0]
	v_pk_mul_f32 v[76:77], v[76:77], v[0:1] op_sel_hi:[1,0]
	flat_store_dwordx4 v[106:107], v[102:105] offset:16
	v_pk_mul_f32 v[74:75], v[74:75], v[0:1] op_sel_hi:[1,0]
	v_pk_mul_f32 v[72:73], v[72:73], v[0:1] op_sel_hi:[1,0]
	v_cvt_pk_bf16_f32 v102, v80, v81
	v_cvt_pk_bf16_f32 v103, v82, v83
	v_cvt_pk_bf16_f32 v104, v76, v77
	v_cvt_pk_bf16_f32 v105, v78, v79
	v_pk_mul_f32 v[70:71], v[70:71], v[0:1] op_sel_hi:[1,0]
	v_pk_mul_f32 v[68:69], v[68:69], v[0:1] op_sel_hi:[1,0]
	flat_store_dwordx4 v[106:107], v[102:105] offset:32
	s_nop 1
	v_cvt_pk_bf16_f32 v102, v72, v73
	v_cvt_pk_bf16_f32 v103, v74, v75
	v_cvt_pk_bf16_f32 v104, v68, v69
	v_cvt_pk_bf16_f32 v105, v70, v71
	flat_store_dwordx4 v[106:107], v[102:105] offset:48
	s_and_saveexec_b64 s[8:9], s[52:53]
	s_cbranch_execz .LBB0_937
	v_mul_f32_e32 v0, v97, v97
	v_mul_f32_e32 v93, v93, v93
	v_mul_f32_e32 v89, v89, v89
	v_mul_f32_e32 v85, v85, v85
	v_fmac_f32_e32 v0, v96, v96
	v_fmac_f32_e32 v93, v92, v92
	v_fmac_f32_e32 v89, v88, v88
	v_fmac_f32_e32 v85, v84, v84
	v_mul_f32_e32 v81, v81, v81
	v_mul_f32_e32 v77, v77, v77
	v_fmac_f32_e32 v0, v98, v98
	v_fmac_f32_e32 v93, v94, v94
	v_fmac_f32_e32 v89, v90, v90
	v_fmac_f32_e32 v85, v86, v86
	v_fmac_f32_e32 v81, v80, v80
	v_fmac_f32_e32 v77, v76, v76
	v_mul_f32_e32 v73, v73, v73
	v_mul_f32_e32 v69, v69, v69
	v_fmac_f32_e32 v0, v99, v99
	v_fmac_f32_e32 v93, v95, v95
	v_fmac_f32_e32 v89, v91, v91
	v_fmac_f32_e32 v85, v87, v87
	v_fmac_f32_e32 v81, v82, v82
	v_fmac_f32_e32 v77, v78, v78
	v_fmac_f32_e32 v73, v72, v72
	v_fmac_f32_e32 v69, v68, v68
	v_add_f32_e32 v0, v0, v93
	v_add_f32_e32 v84, v89, v85
	v_fmac_f32_e32 v81, v83, v83
	v_fmac_f32_e32 v77, v79, v79
	v_fmac_f32_e32 v73, v74, v74
	v_fmac_f32_e32 v69, v70, v70
	v_add_f32_e32 v0, v0, v84
	v_add_f32_e32 v76, v81, v77
	v_fmac_f32_e32 v73, v75, v75
	v_fmac_f32_e32 v69, v71, v71
	v_add_f32_e32 v0, v76, v0
	v_add_f32_e32 v68, v73, v69
	v_add_f32_e32 v0, v68, v0
	v_mov_b32_e32 v68, v0
	s_nop 1
	v_permlane16_swap_b32_e32 v0, v68
	v_add_f32_e32 v0, v0, v68
	v_mov_b32_e32 v68, v0
	s_nop 1
	v_permlane32_swap_b32_e32 v0, v68
	s_and_b64 exec, exec, s[40:41]
	s_cbranch_execz .LBB0_937
	v_cndmask_b32_e64 v69, 4, 5, vcc
	v_cndmask_b32_e32 v71, v143, v3, vcc
	v_cndmask_b32_e32 v70, v142, v2, vcc
	v_lshlrev_b64 v[72:73], v69, v[100:101]
	v_lshl_add_u64 v[70:71], v[70:71], 0, v[72:73]
	v_add_f32_e32 v0, v0, v68
	flat_store_dword v[70:71], v0
; DI u32x2 pack4(f32x4 v) { return u32x2{pack2(v[0], v[1]), pack2(v[2], v[3])}; }
; DI void phase1(const XcdMap xm, const int wv, const Params& p0, int l, char* s0, char* s1, char* s2) {
;     ...
; #pragma unroll
;     for (int mt = 0; mt < 4; ++mt) {
;       const int m = m0 + wr * 64 + mt * 16 + c16;
;       f32x4 s0 = ld4(ssx + (size_t)m * 16), s1 = ld4(ssx + (size_t)m * 16 + 4), s2 = ld4(ssx + (size_t)m * 16 + 8), s3 = ld4(ssx + (size_t)m * 16 + 12);
;       f32x4 st = s0 + s1 + s2 + s3;
;       const float rs = rsqrtf((st[0] + st[1] + st[2] + st[3]) * (1.f / 1024.f) + 1e-6f);
;       float psum = 0.f;
; #pragma unroll
;       for (int nt = 0; nt < 8; nt += 2) {
;         const int n = n0 + wc * 128 + g * 32 + nt * 4;
;         f32x4 v0 = acc[mt][nt] * rs, v1 = acc[mt][nt + 1] * rs;
;         psum += sum4sq(v0) + sum4sq(v1);
;         u32x2 a = pack4(v0), b = pack4(v1);
;         *(u32x4*)(z + (size_t)m * ZC + n) = u32x4{a.x, a.y, b.x, b.y};
;       }
;       const bool isq = (ntile == 8 && wc == 1) || ntile == 9;
;       if (isq || ntile == 10) {
;         psum = xor_sum(psum, 16);
;         psum = xor_sum(psum, 32);
;         if (g == 0) {
;           if (isq) ((float*)(p.ws + WS_SSQ))[(size_t)m * 8 + (ntile == 8 ? 0 : 1 + wc)] = psum;
;           else ((float*)(p.ws + WS_SSKV))[(size_t)m * 4 + wc] = psum;
;         }
;       }
;     }
.LBB0_937:
	s_or_b64 exec, exec, s[8:9]
	v_or_b32_e32 v68, 32, v158
	v_ashrrev_i32_e32 v69, 31, v68
	v_or_b32_e32 v238, 48, v158
	v_ashrrev_i32_e32 v239, 31, v238
	v_lshlrev_b64 v[240:241], 6, v[238:239]
	v_lshl_add_u64 v[240:241], s[44:45], 0, v[240:241]
	flat_load_dwordx4 v[206:209], v[240:241]
	flat_load_dwordx4 v[210:213], v[240:241] offset:16
	flat_load_dwordx4 v[214:217], v[240:241] offset:32
	flat_load_dwordx4 v[218:221], v[240:241] offset:48
	s_waitcnt vmcnt(8)
	v_pk_add_f32 v[222:223], v[222:223], v[226:227]
	v_pk_add_f32 v[224:225], v[224:225], v[228:229]
	v_pk_add_f32 v[222:223], v[222:223], v[230:231]
	v_pk_add_f32 v[224:225], v[224:225], v[232:233]
	v_pk_add_f32 v[222:223], v[222:223], v[234:235]
	v_pk_add_f32 v[224:225], v[224:225], v[236:237]
	v_add_f32_e32 v0, v222, v223
	v_add_f32_e32 v0, v224, v0
	v_add_f32_e32 v0, v225, v0
	v_fmamk_f32 v0, v0, 0x3a800000, v132
	v_cmp_gt_f32_e64 s[42:43], s22, v0
	v_mul_f32_e32 v70, 0x4b800000, v0
	s_nop 0
	v_cndmask_b32_e64 v0, v0, v70, s[42:43]
	v_rsq_f32_e32 v0, v0
	s_nop 0
	v_mul_f32_e32 v70, 0x45800000, v0
	v_cndmask_b32_e64 v0, v0, v70, s[42:43]
	v_mov_b64_e32 v[70:71], s[14:15]
	v_mad_i64_i32 v[74:75], s[8:9], v68, s23, v[70:71]
	v_pk_mul_f32 v[66:67], v[66:67], v[0:1] op_sel_hi:[1,0]
	v_pk_mul_f32 v[64:65], v[64:65], v[0:1] op_sel_hi:[1,0]
	v_pk_mul_f32 v[62:63], v[62:63], v[0:1] op_sel_hi:[1,0]
	v_pk_mul_f32 v[60:61], v[60:61], v[0:1] op_sel_hi:[1,0]
	v_cvt_pk_bf16_f32 v70, v64, v65
	v_cvt_pk_bf16_f32 v71, v66, v67
	v_cvt_pk_bf16_f32 v72, v60, v61
	v_cvt_pk_bf16_f32 v73, v62, v63
	v_lshl_add_u64 v[74:75], v[156:157], 1, v[74:75]
	v_pk_mul_f32 v[58:59], v[58:59], v[0:1] op_sel_hi:[1,0]
	v_pk_mul_f32 v[56:57], v[56:57], v[0:1] op_sel_hi:[1,0]
	v_pk_mul_f32 v[54:55], v[54:55], v[0:1] op_sel_hi:[1,0]
	v_pk_mul_f32 v[52:53], v[52:53], v[0:1] op_sel_hi:[1,0]
	flat_store_dwordx4 v[74:75], v[70:73]
	v_pk_mul_f32 v[50:51], v[50:51], v[0:1] op_sel_hi:[1,0]
	v_pk_mul_f32 v[48:49], v[48:49], v[0:1] op_sel_hi:[1,0]
	v_cvt_pk_bf16_f32 v70, v56, v57
	v_cvt_pk_bf16_f32 v71, v58, v59
	v_cvt_pk_bf16_f32 v72, v52, v53
	v_cvt_pk_bf16_f32 v73, v54, v55
	v_pk_mul_f32 v[46:47], v[46:47], v[0:1] op_sel_hi:[1,0]
	v_pk_mul_f32 v[44:45], v[44:45], v[0:1] op_sel_hi:[1,0]
	flat_store_dwordx4 v[74:75], v[70:73] offset:16
	v_pk_mul_f32 v[42:43], v[42:43], v[0:1] op_sel_hi:[1,0]
	v_pk_mul_f32 v[40:41], v[40:41], v[0:1] op_sel_hi:[1,0]
	v_cvt_pk_bf16_f32 v70, v48, v49
	v_cvt_pk_bf16_f32 v71, v50, v51
	v_cvt_pk_bf16_f32 v72, v44, v45
	v_cvt_pk_bf16_f32 v73, v46, v47
	v_pk_mul_f32 v[38:39], v[38:39], v[0:1] op_sel_hi:[1,0]
	v_pk_mul_f32 v[36:37], v[36:37], v[0:1] op_sel_hi:[1,0]
	flat_store_dwordx4 v[74:75], v[70:73] offset:32
	s_nop 1
	v_cvt_pk_bf16_f32 v70, v40, v41
	v_cvt_pk_bf16_f32 v71, v42, v43
	v_cvt_pk_bf16_f32 v72, v36, v37
	v_cvt_pk_bf16_f32 v73, v38, v39
	flat_store_dwordx4 v[74:75], v[70:73] offset:48
	s_and_saveexec_b64 s[8:9], s[52:53]
	s_cbranch_execz .LBB0_940
	v_mul_f32_e32 v0, v65, v65
	v_mul_f32_e32 v61, v61, v61
	v_mul_f32_e32 v57, v57, v57
	v_mul_f32_e32 v53, v53, v53
	v_fmac_f32_e32 v0, v64, v64
	v_fmac_f32_e32 v61, v60, v60
	v_fmac_f32_e32 v57, v56, v56
	v_fmac_f32_e32 v53, v52, v52
	v_mul_f32_e32 v49, v49, v49
	v_mul_f32_e32 v45, v45, v45
	v_fmac_f32_e32 v0, v66, v66
	v_fmac_f32_e32 v61, v62, v62
	v_fmac_f32_e32 v57, v58, v58
	v_fmac_f32_e32 v53, v54, v54
	v_fmac_f32_e32 v49, v48, v48
	v_fmac_f32_e32 v45, v44, v44
	v_mul_f32_e32 v41, v41, v41
	v_mul_f32_e32 v37, v37, v37
	v_fmac_f32_e32 v0, v67, v67
	v_fmac_f32_e32 v61, v63, v63
	v_fmac_f32_e32 v57, v59, v59
	v_fmac_f32_e32 v53, v55, v55
	v_fmac_f32_e32 v49, v50, v50
	v_fmac_f32_e32 v45, v46, v46
	v_fmac_f32_e32 v41, v40, v40
	v_fmac_f32_e32 v37, v36, v36
	v_add_f32_e32 v0, v0, v61
	v_add_f32_e32 v52, v57, v53
	v_fmac_f32_e32 v49, v51, v51
	v_fmac_f32_e32 v45, v47, v47
	v_fmac_f32_e32 v41, v42, v42
	v_fmac_f32_e32 v37, v38, v38
	v_add_f32_e32 v0, v0, v52
	v_add_f32_e32 v44, v49, v45
	v_fmac_f32_e32 v41, v43, v43
	v_fmac_f32_e32 v37, v39, v39
	v_add_f32_e32 v0, v44, v0
	v_add_f32_e32 v36, v41, v37
	v_add_f32_e32 v0, v36, v0
	v_mov_b32_e32 v36, v0
	s_nop 1
	v_permlane16_swap_b32_e32 v0, v36
	v_add_f32_e32 v0, v0, v36
	v_mov_b32_e32 v36, v0
	s_nop 1
	v_permlane32_swap_b32_e32 v0, v36
	s_and_b64 exec, exec, s[40:41]
	s_cbranch_execz .LBB0_940
	v_cndmask_b32_e64 v37, 4, 5, vcc
	v_cndmask_b32_e32 v39, v143, v3, vcc
	v_cndmask_b32_e32 v38, v142, v2, vcc
	v_lshlrev_b64 v[40:41], v37, v[68:69]
	v_lshl_add_u64 v[38:39], v[38:39], 0, v[40:41]
	v_add_f32_e32 v0, v0, v36
	flat_store_dword v[38:39], v0
; DI u32x2 pack4(f32x4 v) { return u32x2{pack2(v[0], v[1]), pack2(v[2], v[3])}; }
; DI void phase1(const XcdMap xm, const int wv, const Params& p0, int l, char* s0, char* s1, char* s2) {
;     ...
; #pragma unroll
;     for (int mt = 0; mt < 4; ++mt) {
;       const int m = m0 + wr * 64 + mt * 16 + c16;
;       f32x4 s0 = ld4(ssx + (size_t)m * 16), s1 = ld4(ssx + (size_t)m * 16 + 4), s2 = ld4(ssx + (size_t)m * 16 + 8), s3 = ld4(ssx + (size_t)m * 16 + 12);
;       f32x4 st = s0 + s1 + s2 + s3;
;       const float rs = rsqrtf((st[0] + st[1] + st[2] + st[3]) * (1.f / 1024.f) + 1e-6f);
;       float psum = 0.f;
; #pragma unroll
;       for (int nt = 0; nt < 8; nt += 2) {
;         const int n = n0 + wc * 128 + g * 32 + nt * 4;
;         f32x4 v0 = acc[mt][nt] * rs, v1 = acc[mt][nt + 1] * rs;
;         psum += sum4sq(v0) + sum4sq(v1);
;         u32x2 a = pack4(v0), b = pack4(v1);
;         *(u32x4*)(z + (size_t)m * ZC + n) = u32x4{a.x, a.y, b.x, b.y};
;       }
;       const bool isq = (ntile == 8 && wc == 1) || ntile == 9;
;       if (isq || ntile == 10) {
;         psum = xor_sum(psum, 16);
;         psum = xor_sum(psum, 32);
;         if (g == 0) {
;           if (isq) ((float*)(p.ws + WS_SSQ))[(size_t)m * 8 + (ntile == 8 ? 0 : 1 + wc)] = psum;
;           else ((float*)(p.ws + WS_SSKV))[(size_t)m * 4 + wc] = psum;
;         }
;       }
;     }
.LBB0_940:
	s_or_b64 exec, exec, s[8:9]
	v_or_b32_e32 v36, 48, v158
	v_ashrrev_i32_e32 v37, 31, v36
	s_waitcnt vmcnt(4)
	v_pk_add_f32 v[206:207], v[206:207], v[210:211]
	v_pk_add_f32 v[208:209], v[208:209], v[212:213]
	v_pk_add_f32 v[206:207], v[206:207], v[214:215]
	v_pk_add_f32 v[208:209], v[208:209], v[216:217]
	v_pk_add_f32 v[206:207], v[206:207], v[218:219]
	v_pk_add_f32 v[208:209], v[208:209], v[220:221]
	v_add_f32_e32 v0, v206, v207
	v_add_f32_e32 v0, v208, v0
	v_add_f32_e32 v0, v209, v0
	v_fmamk_f32 v0, v0, 0x3a800000, v132
	v_cmp_gt_f32_e64 s[42:43], s22, v0
	v_mul_f32_e32 v38, 0x4b800000, v0
	s_nop 0
	v_cndmask_b32_e64 v0, v0, v38, s[42:43]
	v_rsq_f32_e32 v0, v0
	s_nop 0
	v_mul_f32_e32 v38, 0x45800000, v0
	v_cndmask_b32_e64 v0, v0, v38, s[42:43]
	v_mov_b64_e32 v[38:39], s[14:15]
	v_mad_i64_i32 v[42:43], s[8:9], v36, s23, v[38:39]
	v_pk_mul_f32 v[34:35], v[34:35], v[0:1] op_sel_hi:[1,0]
	v_pk_mul_f32 v[32:33], v[32:33], v[0:1] op_sel_hi:[1,0]
	v_pk_mul_f32 v[30:31], v[30:31], v[0:1] op_sel_hi:[1,0]
	v_pk_mul_f32 v[28:29], v[28:29], v[0:1] op_sel_hi:[1,0]
	v_cvt_pk_bf16_f32 v38, v32, v33
	v_cvt_pk_bf16_f32 v39, v34, v35
	v_cvt_pk_bf16_f32 v40, v28, v29
	v_cvt_pk_bf16_f32 v41, v30, v31
	v_lshl_add_u64 v[42:43], v[156:157], 1, v[42:43]
	v_pk_mul_f32 v[26:27], v[26:27], v[0:1] op_sel_hi:[1,0]
	v_pk_mul_f32 v[24:25], v[24:25], v[0:1] op_sel_hi:[1,0]
	v_pk_mul_f32 v[22:23], v[22:23], v[0:1] op_sel_hi:[1,0]
	v_pk_mul_f32 v[20:21], v[20:21], v[0:1] op_sel_hi:[1,0]
	flat_store_dwordx4 v[42:43], v[38:41]
	v_pk_mul_f32 v[18:19], v[18:19], v[0:1] op_sel_hi:[1,0]
	v_pk_mul_f32 v[16:17], v[16:17], v[0:1] op_sel_hi:[1,0]
	v_cvt_pk_bf16_f32 v38, v24, v25
	v_cvt_pk_bf16_f32 v39, v26, v27
	v_cvt_pk_bf16_f32 v40, v20, v21
	v_cvt_pk_bf16_f32 v41, v22, v23
	v_pk_mul_f32 v[14:15], v[14:15], v[0:1] op_sel_hi:[1,0]
	v_pk_mul_f32 v[12:13], v[12:13], v[0:1] op_sel_hi:[1,0]
	flat_store_dwordx4 v[42:43], v[38:41] offset:16
	v_pk_mul_f32 v[10:11], v[10:11], v[0:1] op_sel_hi:[1,0]
	v_pk_mul_f32 v[8:9], v[8:9], v[0:1] op_sel_hi:[1,0]
	v_cvt_pk_bf16_f32 v38, v16, v17
	v_cvt_pk_bf16_f32 v39, v18, v19
	v_cvt_pk_bf16_f32 v40, v12, v13
	v_cvt_pk_bf16_f32 v41, v14, v15
	v_pk_mul_f32 v[6:7], v[6:7], v[0:1] op_sel_hi:[1,0]
	v_pk_mul_f32 v[4:5], v[4:5], v[0:1] op_sel_hi:[1,0]
	flat_store_dwordx4 v[42:43], v[38:41] offset:32
	s_nop 1
	v_cvt_pk_bf16_f32 v38, v8, v9
	v_cvt_pk_bf16_f32 v39, v10, v11
	v_cvt_pk_bf16_f32 v40, v4, v5
	v_cvt_pk_bf16_f32 v41, v6, v7
	flat_store_dwordx4 v[42:43], v[38:41] offset:48
	s_and_saveexec_b64 s[8:9], s[52:53]
	s_cbranch_execz .LBB0_943
	v_mul_f32_e32 v0, v33, v33
	v_mul_f32_e32 v29, v29, v29
	v_mul_f32_e32 v25, v25, v25
	v_mul_f32_e32 v21, v21, v21
	v_fmac_f32_e32 v0, v32, v32
	v_fmac_f32_e32 v29, v28, v28
	v_fmac_f32_e32 v25, v24, v24
	v_fmac_f32_e32 v21, v20, v20
	v_mul_f32_e32 v17, v17, v17
	v_mul_f32_e32 v13, v13, v13
	v_fmac_f32_e32 v0, v34, v34
	v_fmac_f32_e32 v29, v30, v30
	v_fmac_f32_e32 v25, v26, v26
	v_fmac_f32_e32 v21, v22, v22
	v_fmac_f32_e32 v17, v16, v16
	v_fmac_f32_e32 v13, v12, v12
	v_mul_f32_e32 v9, v9, v9
	v_mul_f32_e32 v5, v5, v5
	v_fmac_f32_e32 v0, v35, v35
	v_fmac_f32_e32 v29, v31, v31
	v_fmac_f32_e32 v25, v27, v27
	v_fmac_f32_e32 v21, v23, v23
	v_fmac_f32_e32 v17, v18, v18
	v_fmac_f32_e32 v13, v14, v14
	v_fmac_f32_e32 v9, v8, v8
	v_fmac_f32_e32 v5, v4, v4
	v_add_f32_e32 v0, v0, v29
	v_add_f32_e32 v20, v25, v21
	v_fmac_f32_e32 v17, v19, v19
	v_fmac_f32_e32 v13, v15, v15
	v_fmac_f32_e32 v9, v10, v10
	v_fmac_f32_e32 v5, v6, v6
	v_add_f32_e32 v0, v0, v20
	v_add_f32_e32 v12, v17, v13
	v_fmac_f32_e32 v9, v11, v11
	v_fmac_f32_e32 v5, v7, v7
	v_add_f32_e32 v0, v12, v0
	v_add_f32_e32 v4, v9, v5
	v_add_f32_e32 v0, v4, v0
	v_mov_b32_e32 v4, v0
	s_nop 1
	v_permlane16_swap_b32_e32 v0, v4
	v_add_f32_e32 v0, v0, v4
	v_mov_b32_e32 v4, v0
	s_nop 1
	v_permlane32_swap_b32_e32 v0, v4
	s_and_b64 exec, exec, s[40:41]
	s_cbranch_execz .LBB0_943
	v_cndmask_b32_e64 v5, 4, 5, vcc
	v_cndmask_b32_e32 v3, v143, v3, vcc
	v_cndmask_b32_e32 v2, v142, v2, vcc
	v_lshlrev_b64 v[6:7], v5, v[36:37]
	v_lshl_add_u64 v[2:3], v[2:3], 0, v[6:7]
	v_add_f32_e32 v0, v0, v4
	flat_store_dword v[2:3], v0
